# v_fma for the MLA running row sum (one instruction instead of two) and permlane32_swap row-max exchange in the cross-attention loop
# speedup vs baseline: 1.0074x; 1.0001x over previous
; #define LAS __attribute__((address_space(3)))
; template <int MODE>
; DI void attn_unit(LAS unsigned char* lds, const AttnArgs a) {
;     ...
;         for (int ks = 0; ks < NKS; ++ks) {
;             const bf16x8 a0 = *(const LAS bf16x8*)(Kc + r32 * KLD + ks * 16 + 8 * hh);
;             const bf16x8 a1 = *(const LAS bf16x8*)(Kc + (32 + r32) * KLD + ks * 16 + 8 * hh);
;             s0 = MFMA32(a0, qf[ks], s0); s1 = MFMA32(a1, qf[ks], s1);
;         }
;         if (MODE == 2) {
;             if (kbase + 63 < q0w) { sb_block<false>(s1, kbase + 32, qi, hh, a.c2, carry); sb_block<false>(s0, kbase, qi, hh, a.c2, carry); }
;             else                  { sb_block<true>(s1, kbase + 32, qi, hh, a.c2, carry);  sb_block<true>(s0, kbase, qi, hh, a.c2, carry); }
;         } else {
;             const bool interior = (MODE == 0) || (MODE == 1 && kbase + 63 <= q0w);
;             float mnew, alpha, ls = 0.f;
;             if (interior) {
; #pragma unroll
;                 for (int i = 0; i < 16; ++i) { s0[i] *= a.c2; s1[i] *= a.c2; }
;                 float mx = max3f(s0[0], s1[0], s0[1]);
;                 mx = max3f(mx, s1[1], s0[2]); mx = max3f(mx, s1[2], s0[3]); mx = max3f(mx, s1[3], s0[4]); mx = max3f(mx, s1[4], s0[5]);
;                 mx = max3f(mx, s1[5], s0[6]); mx = max3f(mx, s1[6], s0[7]); mx = max3f(mx, s1[7], s0[8]); mx = max3f(mx, s1[8], s0[9]);
;                 mx = max3f(mx, s1[9], s0[10]); mx = max3f(mx, s1[10], s0[11]); mx = max3f(mx, s1[11], s0[12]); mx = max3f(mx, s1[12], s0[13]);
;                 mx = max3f(mx, s1[13], s0[14]); mx = max3f(mx, s1[14], s0[15]); mx = fmaxf(mx, s1[15]);
;                 mx = fmaxf(mx, __shfl_xor(mx, 32));
;                 mnew = fmaxf(mrow, mx); alpha = ex2(mrow - mnew);
; #pragma unroll
;                 for (int i = 0; i < 16; ++i) {
;                     const float p0 = ex2(s0[i] - mnew), p1 = ex2(s1[i] - mnew);
;                     s0[i] = p0; s1[i] = p1; ls += p0 + p1;
;                 }
;             } else {
;                 float mx = -1e30f;
; #pragma unroll
;                 for (int i = 0; i < 16; ++i) {
;                     const int k0 = kbase + crow(i, hh), k1 = k0 + 32;
;                     float x0 = s0[i] * a.c2, x1 = s1[i] * a.c2;
;                     bool v0 = true, v1 = true;
;                     if (MODE == 1) { v0 = k0 <= qi; v1 = k1 <= qi; }
;                     if (MODE == 3) {
.LBB0_56:
	s_and_b32 s16, s18, 1
	s_mul_i32 s17, s16, 0x4600
	v_lshl_add_u32 v0, s17, 1, v176
	ds_read_b128 v[2:5], v0
	ds_read_b128 v[6:9], v0 offset:8928
	s_waitcnt lgkmcnt(1)
	v_mfma_f32_32x32x16_bf16 v[80:95], v[2:5], v[112:115], 0
	ds_read_b128 v[2:5], v0 offset:8704
	s_waitcnt lgkmcnt(0)
	v_mfma_f32_32x32x16_bf16 v[96:111], v[2:5], v[112:115], 0
	ds_read_b128 v[2:5], v0 offset:32
	s_waitcnt lgkmcnt(0)
	v_mfma_f32_32x32x16_bf16 v[80:95], v[2:5], v[116:119], v[80:95]
	ds_read_b128 v[2:5], v0 offset:8736
	s_waitcnt lgkmcnt(0)
	v_mfma_f32_32x32x16_bf16 v[96:111], v[2:5], v[116:119], v[96:111]
	ds_read_b128 v[2:5], v0 offset:64
	s_waitcnt lgkmcnt(0)
	v_mfma_f32_32x32x16_bf16 v[80:95], v[2:5], v[120:123], v[80:95]
	ds_read_b128 v[2:5], v0 offset:8768
	s_waitcnt lgkmcnt(0)
	v_mfma_f32_32x32x16_bf16 v[96:111], v[2:5], v[120:123], v[96:111]
	ds_read_b128 v[2:5], v0 offset:96
	s_waitcnt lgkmcnt(0)
	v_mfma_f32_32x32x16_bf16 v[80:95], v[2:5], v[124:127], v[80:95]
	ds_read_b128 v[2:5], v0 offset:8800
	s_waitcnt lgkmcnt(0)
	v_mfma_f32_32x32x16_bf16 v[96:111], v[2:5], v[124:127], v[96:111]
	ds_read_b128 v[2:5], v0 offset:128
	s_waitcnt lgkmcnt(0)
	v_mfma_f32_32x32x16_bf16 v[80:95], v[2:5], v[128:131], v[80:95]
	ds_read_b128 v[2:5], v0 offset:8832
	s_waitcnt lgkmcnt(0)
	v_mfma_f32_32x32x16_bf16 v[96:111], v[2:5], v[128:131], v[96:111]
	ds_read_b128 v[2:5], v0 offset:160
	s_waitcnt lgkmcnt(0)
	v_mfma_f32_32x32x16_bf16 v[80:95], v[2:5], v[132:135], v[80:95]
	ds_read_b128 v[2:5], v0 offset:8864
	s_waitcnt lgkmcnt(0)
	v_mfma_f32_32x32x16_bf16 v[96:111], v[2:5], v[132:135], v[96:111]
	ds_read_b128 v[2:5], v0 offset:192
	s_waitcnt lgkmcnt(0)
	v_mfma_f32_32x32x16_bf16 v[80:95], v[2:5], v[136:139], v[80:95]
	ds_read_b128 v[2:5], v0 offset:8896
	s_waitcnt lgkmcnt(0)
	v_mfma_f32_32x32x16_bf16 v[96:111], v[2:5], v[136:139], v[96:111]
	ds_read_b128 v[2:5], v0 offset:224
	s_waitcnt lgkmcnt(0)
	v_mfma_f32_32x32x16_bf16 v[80:95], v[2:5], v[140:143], v[80:95]
	v_and_b32_e32 v5, 64, v243
	v_xor_b32_e32 v3, 32, v243
	v_add_u32_e32 v5, 64, v5
	v_cmp_lt_i32_e32 vcc, v3, v5
	s_nop 7
	v_mul_f32_e32 v4, 0x3e0293ee, v80
	v_mfma_f32_32x32x16_bf16 v[96:111], v[6:9], v[140:143], v[96:111]
	v_mul_f32_e32 v179, 0x3e0293ee, v81
	v_mul_f32_e32 v7, 0x3e0293ee, v82
	v_mul_f32_e32 v6, 0x3e0293ee, v83
	v_mul_f32_e32 v11, 0x3e0293ee, v84
	v_mul_f32_e32 v8, 0x3e0293ee, v85
	v_mul_f32_e32 v15, 0x3e0293ee, v86
	v_mul_f32_e32 v10, 0x3e0293ee, v87
	s_nop 4
	v_mul_f32_e32 v9, 0x3e0293ee, v96
	v_max3_f32 v2, v4, v9, v179
	v_mul_f32_e32 v0, 0x3e0293ee, v97
	v_max3_f32 v2, v2, v0, v7
	v_mul_f32_e32 v13, 0x3e0293ee, v98
	v_max3_f32 v2, v2, v13, v6
	v_mul_f32_e32 v12, 0x3e0293ee, v99
	v_max3_f32 v2, v2, v12, v11
	v_mul_f32_e32 v81, 0x3e0293ee, v100
	v_max3_f32 v2, v2, v81, v8
	v_mul_f32_e32 v80, 0x3e0293ee, v101
	v_max3_f32 v2, v2, v80, v15
	v_mul_f32_e32 v85, 0x3e0293ee, v102
	v_max3_f32 v2, v2, v85, v10
	v_mul_f32_e32 v84, 0x3e0293ee, v103
	v_mul_f32_e32 v83, 0x3e0293ee, v88
	v_max3_f32 v2, v2, v84, v83
	v_mul_f32_e32 v102, 0x3e0293ee, v104
	v_mul_f32_e32 v14, 0x3e0293ee, v89
	v_max3_f32 v2, v2, v102, v14
	v_mul_f32_e32 v88, 0x3e0293ee, v105
	v_mul_f32_e32 v87, 0x3e0293ee, v90
	v_max3_f32 v2, v2, v88, v87
	v_mul_f32_e32 v101, 0x3e0293ee, v106
	v_mul_f32_e32 v82, 0x3e0293ee, v91
	v_max3_f32 v2, v2, v101, v82
	v_mul_f32_e32 v90, 0x3e0293ee, v107
	v_mul_f32_e32 v100, 0x3e0293ee, v92
	v_max3_f32 v2, v2, v90, v100
	v_mul_f32_e32 v99, 0x3e0293ee, v108
	v_mul_f32_e32 v86, 0x3e0293ee, v93
	v_max3_f32 v2, v2, v99, v86
	v_mul_f32_e32 v97, 0x3e0293ee, v109
	v_mul_f32_e32 v94, 0x3e0293ee, v94
	v_max3_f32 v2, v2, v97, v94
	v_mul_f32_e32 v98, 0x3e0293ee, v110
	v_mul_f32_e32 v92, 0x3e0293ee, v95
	v_max3_f32 v2, v2, v98, v92
	v_mul_f32_e32 v96, 0x3e0293ee, v111
	v_max_f32_e32 v2, v2, v2
	v_cndmask_b32_e32 v3, v243, v3, vcc
	v_max_f32_e32 v2, v2, v96
	v_lshlrev_b32_e32 v3, 2, v3
	v_mov_b32_e32 v5, v2
	v_mov_b32_e32 v89, v177
	s_nop 0
	v_permlane32_swap_b32 v2, v5
	s_waitcnt lgkmcnt(0)
	v_max3_f32 v177, v89, v2, v5
	v_sub_f32_e32 v2, v89, v177
	v_exp_f32_e32 v2, v2
	s_nop 0
	v_cmp_gt_f32_e32 vcc, 1.0, v2
	s_cbranch_vccz .LBB0_58
	v_pk_mul_f32 v[78:79], v[78:79], v[2:3] op_sel_hi:[1,0]
	v_pk_mul_f32 v[76:77], v[76:77], v[2:3] op_sel_hi:[1,0]
	v_pk_mul_f32 v[74:75], v[74:75], v[2:3] op_sel_hi:[1,0]
	v_pk_mul_f32 v[72:73], v[72:73], v[2:3] op_sel_hi:[1,0]
	v_pk_mul_f32 v[70:71], v[70:71], v[2:3] op_sel_hi:[1,0]
	v_pk_mul_f32 v[68:69], v[68:69], v[2:3] op_sel_hi:[1,0]
	v_pk_mul_f32 v[66:67], v[66:67], v[2:3] op_sel_hi:[1,0]
	v_pk_mul_f32 v[64:65], v[64:65], v[2:3] op_sel_hi:[1,0]
	v_pk_mul_f32 v[62:63], v[62:63], v[2:3] op_sel_hi:[1,0]
	v_pk_mul_f32 v[60:61], v[60:61], v[2:3] op_sel_hi:[1,0]
	v_pk_mul_f32 v[58:59], v[58:59], v[2:3] op_sel_hi:[1,0]
	v_pk_mul_f32 v[56:57], v[56:57], v[2:3] op_sel_hi:[1,0]
	v_pk_mul_f32 v[54:55], v[54:55], v[2:3] op_sel_hi:[1,0]
	v_pk_mul_f32 v[52:53], v[52:53], v[2:3] op_sel_hi:[1,0]
	v_pk_mul_f32 v[50:51], v[50:51], v[2:3] op_sel_hi:[1,0]
	v_pk_mul_f32 v[48:49], v[48:49], v[2:3] op_sel_hi:[1,0]
	v_pk_mul_f32 v[46:47], v[46:47], v[2:3] op_sel_hi:[1,0]
	v_pk_mul_f32 v[44:45], v[44:45], v[2:3] op_sel_hi:[1,0]
	v_pk_mul_f32 v[42:43], v[42:43], v[2:3] op_sel_hi:[1,0]
	v_pk_mul_f32 v[40:41], v[40:41], v[2:3] op_sel_hi:[1,0]
	v_pk_mul_f32 v[38:39], v[38:39], v[2:3] op_sel_hi:[1,0]
	v_pk_mul_f32 v[36:37], v[36:37], v[2:3] op_sel_hi:[1,0]
	v_pk_mul_f32 v[34:35], v[34:35], v[2:3] op_sel_hi:[1,0]
	v_pk_mul_f32 v[32:33], v[32:33], v[2:3] op_sel_hi:[1,0]
	v_pk_mul_f32 v[30:31], v[30:31], v[2:3] op_sel_hi:[1,0]
	v_pk_mul_f32 v[28:29], v[28:29], v[2:3] op_sel_hi:[1,0]
	v_pk_mul_f32 v[26:27], v[26:27], v[2:3] op_sel_hi:[1,0]
	v_pk_mul_f32 v[24:25], v[24:25], v[2:3] op_sel_hi:[1,0]
	v_pk_mul_f32 v[22:23], v[22:23], v[2:3] op_sel_hi:[1,0]
	v_pk_mul_f32 v[20:21], v[20:21], v[2:3] op_sel_hi:[1,0]
	v_pk_mul_f32 v[18:19], v[18:19], v[2:3] op_sel_hi:[1,0]
	v_pk_mul_f32 v[16:17], v[16:17], v[2:3] op_sel_hi:[1,0]

; template <int MODE>
; DI void attn_unit(LAS unsigned char* lds, const AttnArgs a) {
;     ...
; #pragma unroll
;                 for (int i = 0; i < 16; ++i) {
;                     const float p0 = ex2(s0[i] - mnew), p1 = ex2(s1[i] - mnew);
;                     s0[i] = p0; s1[i] = p1; ls += p0 + p1;
;                 }
;             } else {
;                 float mx = -1e30f;
; #pragma unroll
;                 for (int i = 0; i < 16; ++i) {
;                     const int k0 = kbase + crow(i, hh), k1 = k0 + 32;
;                     float x0 = s0[i] * a.c2, x1 = s1[i] * a.c2;
;                     bool v0 = true, v1 = true;
;                     if (MODE == 1) { v0 = k0 <= qi; v1 = k1 <= qi; }
;                     if (MODE == 3) {
;                         const int st0 = qi - k0, st1 = qi - k1;
;                         v0 = (st0 >= 0) && (st0 <= 128) && (k0 >= 0); v1 = (st1 >= 0) && (st1 <= 128) && (k1 >= 0);
;                         x0 += biasL[min(max(st0, 0), 128)]; x1 += biasL[min(max(st1, 0), 128)];
;                     }
;                     x0 = v0 ? x0 : -1e30f; x1 = v1 ? x1 : -1e30f;
;                     s0[i] = x0; s1[i] = x1; mx = fmaxf(mx, fmaxf(x0, x1));
;                 }
;                 mx = fmaxf(mx, __shfl_xor(mx, 32));
;                 mnew = fmaxf(mrow, mx); alpha = ex2(mrow - mnew);
; #pragma unroll
;                 for (int i = 0; i < 16; ++i) {
;                     const float p0 = (s0[i] > -1e29f) ? ex2(s0[i] - mnew) : 0.f, p1 = (s1[i] > -1e29f) ? ex2(s1[i] - mnew) : 0.f;
;                     s0[i] = p0; s1[i] = p1; ls += p0 + p1;
;                 }
;             }
;             mrow = mnew;
;             lrow = lrow * alpha + ls;
;             if (__ballot(alpha < 1.0f) != 0ull) {
; #pragma unroll
;                 for (int d = 0; d < NDB; ++d)
; #pragma unroll
;                     for (int i = 0; i < 16; ++i) o[d][i] *= alpha;
;             }
;         }
;         const bf16x8 pb00 = pack8(s0, 0), pb01 = pack8(s0, 1), pb10 = pack8(s1, 0), pb11 = pack8(s1, 1);
; #pragma unroll
;         for (int d = 0; d < NDB; ++d) {
;             const LAS bf16_t* vp = Vc + (d * 32 + r32) * VLD;
;             const int sw = SWZ ? ((((d * 32 + r32) >> 3) & 7) << 2) : 0;
;     ...
;             o[d] = MFMA32(VFRAG(0), pb00, o[d]);
;             o[d] = MFMA32(VFRAG(16), pb01, o[d]);
;             o[d] = MFMA32(VFRAG(32), pb10, o[d]);
.Lmla_f_nors:
	v_exp_f32_e32 v48, v48
	v_exp_f32_e32 v49, v49
	v_exp_f32_e32 v50, v50
	v_exp_f32_e32 v51, v51
	v_exp_f32_e32 v52, v52
	v_exp_f32_e32 v53, v53
	v_exp_f32_e32 v54, v54
	v_exp_f32_e32 v55, v55
	v_pk_add_f32 v[160:161], v[48:49], v[50:51]
	v_pk_add_f32 v[162:163], v[52:53], v[54:55]
	v_cvt_pk_bf16_f32 v4, v48, v49
	v_cvt_pk_bf16_f32 v5, v50, v51
	v_cvt_pk_bf16_f32 v6, v52, v53
	v_cvt_pk_bf16_f32 v7, v54, v55
	s_nop 1
	s_waitcnt lgkmcnt(4)
	v_mfma_f32_32x32x16_bf16 v[32:47], v[64:67], v[4:7], v[32:47]
	v_mfma_f32_32x32x16_bf16 v[16:31], v[68:71], v[4:7], v[16:31]
	ds_read_b64_tr_b16 v[64:65], v158 offset:17664
	ds_read_b64_tr_b16 v[66:67], v158 offset:18688
	ds_read_b64_tr_b16 v[68:69], v159 offset:17664
	ds_read_b64_tr_b16 v[70:71], v159 offset:18688
	v_fma_f32 v56, v56, s6, -v231
	v_fma_f32 v57, v57, s6, -v231
	v_fma_f32 v58, v58, s6, -v231
	v_fma_f32 v59, v59, s6, -v231
	v_fma_f32 v60, v60, s6, -v231
	v_fma_f32 v61, v61, s6, -v231
	v_fma_f32 v62, v62, s6, -v231
	v_fma_f32 v63, v63, s6, -v231
	v_exp_f32_e32 v56, v56
	v_exp_f32_e32 v57, v57
	v_exp_f32_e32 v58, v58
	v_exp_f32_e32 v59, v59
	v_exp_f32_e32 v60, v60
	v_exp_f32_e32 v61, v61
	v_exp_f32_e32 v62, v62
	v_exp_f32_e32 v63, v63
	v_pk_add_f32 v[160:161], v[160:161], v[56:57]
	v_pk_add_f32 v[162:163], v[162:163], v[58:59]
	v_pk_add_f32 v[160:161], v[160:161], v[60:61]
	v_pk_add_f32 v[162:163], v[162:163], v[62:63]
	v_cvt_pk_bf16_f32 v8, v56, v57
	v_cvt_pk_bf16_f32 v9, v58, v59
	v_cvt_pk_bf16_f32 v10, v60, v61
	v_cvt_pk_bf16_f32 v11, v62, v63
	s_nop 1
	s_waitcnt lgkmcnt(4)
	v_mfma_f32_32x32x16_bf16 v[32:47], v[72:75], v[8:11], v[32:47]
	v_mfma_f32_32x32x16_bf16 v[16:31], v[76:79], v[8:11], v[16:31]
	ds_read_b64_tr_b16 v[72:73], v158 offset:19712
	ds_read_b64_tr_b16 v[74:75], v158 offset:20736
	ds_read_b64_tr_b16 v[76:77], v159 offset:19712
	ds_read_b64_tr_b16 v[78:79], v159 offset:20736
	v_fma_f32 v80, v80, s6, -v231
	v_fma_f32 v81, v81, s6, -v231
	v_fma_f32 v82, v82, s6, -v231
	v_fma_f32 v83, v83, s6, -v231
	v_fma_f32 v84, v84, s6, -v231
	v_fma_f32 v85, v85, s6, -v231
	v_fma_f32 v86, v86, s6, -v231
	v_fma_f32 v87, v87, s6, -v231
	v_exp_f32_e32 v80, v80
	v_exp_f32_e32 v81, v81
	v_exp_f32_e32 v82, v82
	v_exp_f32_e32 v83, v83
	v_exp_f32_e32 v84, v84
	v_exp_f32_e32 v85, v85
	v_exp_f32_e32 v86, v86
	v_exp_f32_e32 v87, v87
	v_pk_add_f32 v[160:161], v[160:161], v[80:81]
	v_pk_add_f32 v[162:163], v[162:163], v[82:83]
	v_pk_add_f32 v[160:161], v[160:161], v[84:85]
	v_pk_add_f32 v[162:163], v[162:163], v[86:87]
	v_cvt_pk_bf16_f32 v12, v80, v81
	v_cvt_pk_bf16_f32 v13, v82, v83
	v_cvt_pk_bf16_f32 v14, v84, v85
	v_cvt_pk_bf16_f32 v15, v86, v87
	s_nop 1
	s_waitcnt lgkmcnt(4)
	v_mfma_f32_32x32x16_bf16 v[32:47], v[64:67], v[12:15], v[32:47]
	v_mfma_f32_32x32x16_bf16 v[16:31], v[68:71], v[12:15], v[16:31]
	v_fma_f32 v88, v88, s6, -v231
	v_fma_f32 v89, v89, s6, -v231
	v_fma_f32 v90, v90, s6, -v231
	v_fma_f32 v91, v91, s6, -v231
	v_fma_f32 v92, v92, s6, -v231
	v_fma_f32 v93, v93, s6, -v231
	v_fma_f32 v94, v94, s6, -v231
	v_fma_f32 v95, v95, s6, -v231
	v_exp_f32_e32 v88, v88
	v_exp_f32_e32 v89, v89
	v_exp_f32_e32 v90, v90
	v_exp_f32_e32 v91, v91
	v_exp_f32_e32 v92, v92
	v_exp_f32_e32 v93, v93
	v_exp_f32_e32 v94, v94
	v_exp_f32_e32 v95, v95
	v_pk_add_f32 v[160:161], v[160:161], v[88:89]
	v_pk_add_f32 v[162:163], v[162:163], v[90:91]
	v_pk_add_f32 v[160:161], v[160:161], v[92:93]
	v_pk_add_f32 v[162:163], v[162:163], v[94:95]
	v_cvt_pk_bf16_f32 v154, v88, v89
	v_cvt_pk_bf16_f32 v155, v90, v91
	v_cvt_pk_bf16_f32 v156, v92, v93
	v_cvt_pk_bf16_f32 v157, v94, v95
	s_nop 1
	s_waitcnt lgkmcnt(0)
	v_mfma_f32_32x32x16_bf16 v[32:47], v[72:75], v[154:157], v[32:47]
	v_mfma_f32_32x32x16_bf16 v[16:31], v[76:79], v[154:157], v[16:31]
	v_pk_add_f32 v[160:161], v[160:161], v[162:163]
	v_add_f32_e32 v160, v160, v161
	v_fma_f32 v230, v230, v2, v160
	s_branch .Lmla_pvj
